# attention: V-tile LDS stage writes back to paired ds_write2_b64 (4 LDS instructions fewer per 256 keys) using the VGPRs the scalar-base loads freed
# baseline (speedup 1.0000x reference)
; DI float bflo(unsigned u) { return __uint_as_float(u << 16); }
; DI float bfhi(unsigned u) { return __uint_as_float(u & 0xffff0000u); }
; DI f32x16 zero16() { f32x16 z; for (int i = 0; i < 16; ++i) z[i] = 0.f; return z; }
; DI void phase_attn(const Params& p, int hf, bool skipctx, char* smem, int& rot) {
;     ...
;       uint4 qu[6];
; #pragma unroll
;       for (int ks = 0; ks < 6; ++ks) qu[ks] = *(const uint4*)(Qb + tq * 768 + head * 96 + ks * 16 + h * 8);
; #pragma unroll
;       for (int ks = 0; ks < 4; ++ks) {
;         const uint4 u = qu[ks];
;         qf[ks] = pack8(bflo(u.x) * QSCALE, bfhi(u.x) * QSCALE, bflo(u.y) * QSCALE, bfhi(u.y) * QSCALE, bflo(u.z) * QSCALE, bfhi(u.z) * QSCALE, bflo(u.w) * QSCALE, bfhi(u.w) * QSCALE);
;       }
;       const unsigned a1[4] = {qu[4].x, qu[4].y, qu[4].z, qu[4].w}, a2[4] = {qu[5].x, qu[5].y, qu[5].z, qu[5].w};
;       float o1[8], o2[8];
;       const int sq_ = s0 + w * 32 + r;
; #pragma unroll
;       for (int e = 0; e < 8; ++e) {
;         const float x1 = ((e & 1) ? bfhi(a1[e >> 1]) : bflo(a1[e >> 1])) * QSCALE;
;         const float x2 = ((e & 1) ? bfhi(a2[e >> 1]) : bflo(a2[e >> 1])) * QSCALE;
;         float cs = 1.f, sn = 0.f;
;         if (sq_ >= LC) { cs = axc[(sq_ - LC) * 16 + 8 * h + e]; sn = axs[(sq_ - LC) * 16 + 8 * h + e]; }
;         o1[e] = x1 * cs - x2 * sn; o2[e] = x1 * sn + x2 * cs;
;       }
;       qf[4] = pack8(o1[0], o1[1], o1[2], o1[3], o1[4], o1[5], o1[6], o1[7]);
;       qf[5] = pack8(o2[0], o2[1], o2[2], o2[3], o2[4], o2[5], o2[6], o2[7]);
;     }
;     const bf16_t* Kg = Kb + (size_t)(bl * 8 + head) * S * 96;
;     const bf16_t* Vg = VTb + (size_t)(bl * 8 + head) * 64 * S;
;     f32x16 o[2]; o[0] = zero16(); o[1] = zero16();
;     float m_run = -1e30f, l_run = 0.f;
;     uint4 ak0, ak1, ak2, av0, av1, bk0, bk1, bk2, bv0, bv1;
;     const int kr0 = tid / 12, kc0 = tid - kr0 * 12, kr1 = (tid + 512) / 12, kc1 = (tid + 512) - kr1 * 12, kr2 = (tid + 1024) / 12, kc2 = (tid + 1024) - kr2 * 12;
.LBB0_794:
	s_or_b64 exec, exec, s[26:27]
	s_waitcnt vmcnt(0)
	v_lshlrev_b32_e32 v27, 16, v23
	v_lshlrev_b32_e32 v26, 16, v19
	v_pk_mul_f32 v[26:27], v[26:27], s[48:49] op_sel_hi:[1,0]
	v_lshlrev_b32_e32 v47, 16, v22
	v_pk_mul_f32 v[28:29], v[26:27], v[30:31] op_sel:[0,1] op_sel_hi:[1,0]
	v_pk_mul_f32 v[26:27], v[26:27], v[30:31]
	v_and_b32_e32 v30, 0xffff0000, v19
	v_lshlrev_b32_e32 v46, 16, v18
	v_and_b32_e32 v19, 0xffff0000, v22
	v_and_b32_e32 v18, 0xffff0000, v18
	v_and_b32_e32 v31, 0xffff0000, v23
	v_pk_mul_f32 v[46:47], v[46:47], s[48:49] op_sel_hi:[1,0]
	v_pk_mul_f32 v[22:23], v[18:19], s[48:49] op_sel_hi:[1,0]
	v_pk_mul_f32 v[48:49], v[46:47], v[42:43] op_sel:[0,1] op_sel_hi:[1,0]
	v_pk_mul_f32 v[42:43], v[46:47], v[42:43]
	v_pk_mul_f32 v[18:19], v[22:23], v[40:41] op_sel:[0,1] op_sel_hi:[1,0]
	v_pk_mul_f32 v[22:23], v[22:23], v[40:41]
	v_mov_b32_e32 v40, v42
	v_mov_b32_e32 v41, v22
	v_mov_b32_e32 v22, v43
	v_pk_add_f32 v[22:23], v[40:41], v[22:23]
	v_lshlrev_b32_e32 v41, 16, v21
	v_lshlrev_b32_e32 v40, 16, v17
	v_pk_mul_f32 v[40:41], v[40:41], s[48:49] op_sel_hi:[1,0]
	v_mov_b32_e32 v46, v48
	v_mov_b32_e32 v47, v18
	v_mov_b32_e32 v18, v49
	v_pk_mul_f32 v[42:43], v[40:41], v[32:33] op_sel:[0,1] op_sel_hi:[1,0]
	v_pk_mul_f32 v[40:41], v[40:41], v[32:33]
	v_and_b32_e32 v33, 0xffff0000, v21
	v_and_b32_e32 v32, 0xffff0000, v17
	v_pk_add_f32 v[18:19], v[46:47], v[18:19] neg_lo:[0,1] neg_hi:[0,1]
	v_pk_mul_f32 v[46:47], v[32:33], s[48:49] op_sel_hi:[1,0]
	v_mov_b32_e32 v48, v42
	v_pk_mul_f32 v[32:33], v[46:47], v[34:35] op_sel:[0,1] op_sel_hi:[1,0]
	v_pk_mul_f32 v[34:35], v[46:47], v[34:35]
	v_mov_b32_e32 v49, v32
	v_mov_b32_e32 v32, v43
	v_mov_b32_e32 v42, v40
	v_mov_b32_e32 v43, v34
	v_mov_b32_e32 v34, v41
	v_lshlrev_b32_e32 v41, 16, v20
	v_lshlrev_b32_e32 v40, 16, v16
	v_and_b32_e32 v17, 0xffff0000, v20
	v_and_b32_e32 v16, 0xffff0000, v16
	v_pk_mul_f32 v[40:41], v[40:41], s[48:49] op_sel_hi:[1,0]
	v_pk_mul_f32 v[20:21], v[16:17], s[48:49] op_sel_hi:[1,0]
	v_pk_add_f32 v[34:35], v[42:43], v[34:35]
	v_pk_mul_f32 v[42:43], v[40:41], v[38:39] op_sel:[0,1] op_sel_hi:[1,0]
	v_pk_mul_f32 v[38:39], v[40:41], v[38:39]
	v_pk_mul_f32 v[16:17], v[20:21], v[36:37] op_sel:[0,1] op_sel_hi:[1,0]
	v_pk_mul_f32 v[20:21], v[20:21], v[36:37]
	v_mov_b32_e32 v36, v38
	v_mov_b32_e32 v37, v20
	v_mov_b32_e32 v20, v39
	v_pk_add_f32 v[20:21], v[36:37], v[20:21]
	v_lshlrev_b32_e32 v36, 16, v12
	v_and_b32_e32 v37, 0xffff0000, v12
	v_lshlrev_b32_e32 v12, 16, v13
	v_and_b32_e32 v13, 0xffff0000, v13
	v_pk_mul_f32 v[12:13], v[12:13], s[48:49] op_sel_hi:[1,0]
	v_lshlrev_b32_e32 v38, 16, v14
	v_cvt_pk_bf16_f32 v65, v12, v13
	v_lshlrev_b32_e32 v12, 16, v8
	v_and_b32_e32 v13, 0xffff0000, v8
	v_lshlrev_b32_e32 v8, 16, v9
	v_and_b32_e32 v9, 0xffff0000, v9
	v_pk_mul_f32 v[8:9], v[8:9], s[48:49] op_sel_hi:[1,0]
	v_and_b32_e32 v39, 0xffff0000, v14
	v_cvt_pk_bf16_f32 v69, v8, v9
	v_lshlrev_b32_e32 v8, 16, v4
	v_and_b32_e32 v9, 0xffff0000, v4
	v_lshlrev_b32_e32 v4, 16, v5
	v_and_b32_e32 v5, 0xffff0000, v5
	v_lshlrev_b32_e32 v14, 16, v15
	v_and_b32_e32 v15, 0xffff0000, v15
	v_pk_mul_f32 v[4:5], v[4:5], s[48:49] op_sel_hi:[1,0]
	s_mov_b32 s16, 0x2aaaaaab
	v_pk_mul_f32 v[14:15], v[14:15], s[48:49] op_sel_hi:[1,0]
	v_cvt_pk_bf16_f32 v73, v4, v5
	v_mul_hi_i32 v4, v160, s16
	v_cvt_pk_bf16_f32 v67, v14, v15
	v_lshlrev_b32_e32 v14, 16, v10
	v_and_b32_e32 v15, 0xffff0000, v10
	v_lshlrev_b32_e32 v10, 16, v11
	v_and_b32_e32 v11, 0xffff0000, v11
	v_lshrrev_b32_e32 v5, 31, v4
	v_ashrrev_i32_e32 v4, 1, v4
	v_pk_mul_f32 v[10:11], v[10:11], s[48:49] op_sel_hi:[1,0]
	v_add_u32_e32 v45, v4, v5
	v_cvt_pk_bf16_f32 v71, v10, v11
	v_lshlrev_b32_e32 v10, 16, v6
	v_and_b32_e32 v11, 0xffff0000, v6
	v_lshlrev_b32_e32 v6, 16, v7
	v_and_b32_e32 v7, 0xffff0000, v7
	v_mad_u64_u32 v[4:5], s[38:39], v45, -12, v[160:161]
	v_add_u32_e32 v164, 0x200, v160
	v_pk_mul_f32 v[6:7], v[6:7], s[48:49] op_sel_hi:[1,0]
	v_mul_hi_i32 v5, v164, s16
	v_cvt_pk_bf16_f32 v75, v6, v7
	v_lshrrev_b32_e32 v6, 31, v5
	v_ashrrev_i32_e32 v5, 1, v5
	s_mul_i32 s15, s4, 0xcc000
	v_add_u32_e32 v5, v5, v6
	v_pk_mul_f32 v[38:39], v[38:39], s[48:49] op_sel_hi:[1,0]
	v_pk_mul_f32 v[14:15], v[14:15], s[48:49] op_sel_hi:[1,0]
	s_mul_hi_i32 s5, s4, 0xcc000
	s_add_u32 s26, s90, s15
	v_mad_u64_u32 v[6:7], s[38:39], v5, -12, v[164:165]
	v_add_u32_e32 v162, 0x400, v160
	v_cvt_pk_bf16_f32 v66, v38, v39
	v_cvt_pk_bf16_f32 v70, v14, v15
	v_pk_mul_f32 v[8:9], v[8:9], s[48:49] op_sel_hi:[1,0]
	v_pk_mul_f32 v[10:11], v[10:11], s[48:49] op_sel_hi:[1,0]
	s_addc_u32 s27, s91, s5
	v_mul_hi_i32 v7, v162, s16
	v_lshlrev_b32_e32 v14, 3, v4
	v_lshlrev_b32_e32 v38, 3, v6
	v_pk_mul_f32 v[36:37], v[36:37], s[48:49] op_sel_hi:[1,0]
	v_pk_mul_f32 v[12:13], v[12:13], s[48:49] op_sel_hi:[1,0]
	v_cvt_pk_bf16_f32 v72, v8, v9
	v_cvt_pk_bf16_f32 v74, v10, v11
	v_lshrrev_b32_e32 v8, 31, v7
	v_ashrrev_i32_e32 v7, 1, v7
	v_mov_b64_e32 v[10:11], s[26:27]
	v_ashrrev_i32_e32 v15, 31, v14
	v_ashrrev_i32_e32 v39, 31, v38
	v_cvt_pk_bf16_f32 v64, v36, v37
	v_cvt_pk_bf16_f32 v68, v12, v13
	v_add_u32_e32 v7, v7, v8
	v_mad_i64_i32 v[12:13], s[26:27], v45, s17, v[10:11]
	v_lshlrev_b64 v[14:15], 1, v[14:15]
	v_mad_i64_i32 v[36:37], s[26:27], v5, s17, v[10:11]
	v_lshlrev_b64 v[38:39], 1, v[38:39]
	v_mad_u64_u32 v[8:9], s[38:39], v7, -12, v[162:163]
	v_lshl_add_u64 v[12:13], v[12:13], 0, v[14:15]
	v_lshl_add_u64 v[36:37], v[36:37], 0, v[38:39]
	s_barrier
; DI float bflo(unsigned u) { return __uint_as_float(u << 16); }
; DI float bfhi(unsigned u) { return __uint_as_float(u & 0xffff0000u); }
; DI f32x16 zero16() { f32x16 z; for (int i = 0; i < 16; ++i) z[i] = 0.f; return z; }
; DI void phase_attn(const Params& p, int hf, bool skipctx, char* smem, int& rot) {
;     ...
;       const unsigned a1[4] = {qu[4].x, qu[4].y, qu[4].z, qu[4].w}, a2[4] = {qu[5].x, qu[5].y, qu[5].z, qu[5].w};
;       float o1[8], o2[8];
;       const int sq_ = s0 + w * 32 + r;
; #pragma unroll
;       for (int e = 0; e < 8; ++e) {
;         const float x1 = ((e & 1) ? bfhi(a1[e >> 1]) : bflo(a1[e >> 1])) * QSCALE;
;         const float x2 = ((e & 1) ? bfhi(a2[e >> 1]) : bflo(a2[e >> 1])) * QSCALE;
;         float cs = 1.f, sn = 0.f;
;         if (sq_ >= LC) { cs = axc[(sq_ - LC) * 16 + 8 * h + e]; sn = axs[(sq_ - LC) * 16 + 8 * h + e]; }
;         o1[e] = x1 * cs - x2 * sn; o2[e] = x1 * sn + x2 * cs;
;       }
;       qf[4] = pack8(o1[0], o1[1], o1[2], o1[3], o1[4], o1[5], o1[6], o1[7]);
;       qf[5] = pack8(o2[0], o2[1], o2[2], o2[3], o2[4], o2[5], o2[6], o2[7]);
;     }
;     const bf16_t* Kg = Kb + (size_t)(bl * 8 + head) * S * 96;
;     const bf16_t* Vg = VTb + (size_t)(bl * 8 + head) * 64 * S;
;     f32x16 o[2]; o[0] = zero16(); o[1] = zero16();
;     float m_run = -1e30f, l_run = 0.f;
;     uint4 ak0, ak1, ak2, av0, av1, bk0, bk1, bk2, bv0, bv1;
;     const int kr0 = tid / 12, kc0 = tid - kr0 * 12, kr1 = (tid + 512) / 12, kc1 = (tid + 512) - kr1 * 12, kr2 = (tid + 1024) / 12, kc2 = (tid + 1024) - kr2 * 12;
;     const int vr0 = tid >> 4, vr1 = (tid + 512) >> 4, vc = tid & 15;
	global_load_dwordx4 v[76:79], v[12:13], off
	global_load_dwordx4 v[80:83], v[36:37], off
	v_lshlrev_b32_e32 v36, 3, v8
	s_mul_i32 s15, s4, 0x88000
	v_readlane_b32 s36, v252, 5
	v_ashrrev_i32_e32 v37, 31, v36
	s_mul_hi_i32 s5, s4, 0x88000
	v_readlane_b32 s37, v252, 6
	s_add_u32 s36, s36, s15
	v_mad_i64_i32 v[12:13], s[26:27], v7, s17, v[10:11]
	v_lshlrev_b64 v[36:37], 1, v[36:37]
	s_addc_u32 s37, s37, s5
	v_lshl_add_u64 v[12:13], v[12:13], 0, v[36:37]
	v_mov_b32_e32 v40, v42
	v_mov_b32_e32 v41, v16
	v_mov_b32_e32 v16, v43
	v_ashrrev_i32_e32 v9, 4, v160
	v_ashrrev_i32_e32 v50, 4, v164
	global_load_dwordx4 v[84:87], v[12:13], off
	v_mov_b64_e32 v[12:13], s[36:37]
	s_movk_i32 s16, 0x2200
	v_lshlrev_b32_e32 v165, 4, v160
	v_cvt_pk_bf16_f32 v100, v20, v21
	v_add_u32_e32 v20, 0x80, v5
	v_pk_add_f32 v[16:17], v[40:41], v[16:17] neg_lo:[0,1] neg_hi:[0,1]
	v_mad_i64_i32 v[40:41], s[26:27], v9, s16, v[12:13]
	v_and_b32_e32 v42, 0xf0, v165
	v_mov_b32_e32 v43, v221
	v_mad_i64_i32 v[12:13], s[26:27], v50, s16, v[12:13]
	v_cvt_pk_bf16_f32 v98, v18, v19
	v_cvt_pk_bf16_f32 v102, v22, v23
	v_add_u32_e32 v18, 0x80, v45
	v_mad_i64_i32 v[20:21], s[26:27], v20, s17, v[10:11]
	v_add_u32_e32 v22, 0x80, v7
	v_lshl_add_u64 v[40:41], v[40:41], 0, v[42:43]
	v_lshl_add_u64 v[12:13], v[12:13], 0, v[42:43]
	v_mad_i64_i32 v[18:19], s[26:27], v18, s17, v[10:11]
	v_lshl_add_u64 v[20:21], v[20:21], 0, v[38:39]
	v_mad_i64_i32 v[10:11], s[26:27], v22, s17, v[10:11]
	global_load_dwordx4 v[92:95], v[40:41], off
	global_load_dwordx4 v[104:107], v[12:13], off
	v_lshl_add_u64 v[18:19], v[18:19], 0, v[14:15]
	v_lshl_add_u64 v[10:11], v[10:11], 0, v[36:37]
	global_load_dwordx4 v[108:111], v[20:21], off
	global_load_dwordx4 v[116:119], v[10:11], off
	global_load_dwordx4 v[120:123], v[40:41], off offset:256
	global_load_dwordx4 v[112:115], v[18:19], off
	global_load_dwordx4 v[124:127], v[12:13], off offset:256
	v_lshlrev_b32_e32 v46, 16, v0
	v_and_b32_e32 v47, 0xffff0000, v0
	v_lshlrev_b32_e32 v0, 16, v1
	v_and_b32_e32 v1, 0xffff0000, v1
	v_pk_mul_f32 v[30:31], v[30:31], s[48:49] op_sel_hi:[1,0]
	v_pk_add_f32 v[32:33], v[48:49], v[32:33] neg_lo:[0,1] neg_hi:[0,1]
	v_pk_mul_f32 v[0:1], v[0:1], s[48:49] op_sel_hi:[1,0]
	v_lshlrev_b32_e32 v48, 16, v2
	v_and_b32_e32 v49, 0xffff0000, v2
	v_lshlrev_b32_e32 v2, 16, v3
	v_and_b32_e32 v3, 0xffff0000, v3
	v_pk_mul_f32 v[2:3], v[2:3], s[48:49] op_sel_hi:[1,0]
	v_cvt_pk_bf16_f32 v89, v0, v1
	v_pk_mul_f32 v[0:1], v[30:31], v[24:25] op_sel:[0,1] op_sel_hi:[1,0]
	v_cvt_pk_bf16_f32 v91, v2, v3
	v_mov_b32_e32 v2, v28
	v_mov_b32_e32 v3, v0
	v_mov_b32_e32 v0, v29
	v_pk_add_f32 v[0:1], v[2:3], v[0:1] neg_lo:[0,1] neg_hi:[0,1]
	v_pk_mul_f32 v[2:3], v[30:31], v[24:25]
	v_mul_lo_u32 v10, v45, s97
	v_mov_b32_e32 v24, v26
	v_mov_b32_e32 v25, v2
	v_mov_b32_e32 v2, v27
	v_add_u32_e32 v10, 0, v10
	v_lshlrev_b32_e32 v4, 4, v4
	v_pk_add_f32 v[2:3], v[24:25], v[2:3]
	v_add_u32_e32 v176, v10, v4
	v_mul_lo_u32 v4, v5, s97
	v_cvt_pk_bf16_f32 v103, v2, v3
	v_mad_i64_i32 v[2:3], s[26:27], v5, s17, 0
	v_add_u32_e32 v4, 0, v4
	v_lshlrev_b32_e32 v5, 4, v6
	v_add_u32_e32 v177, v4, v5
	v_mul_lo_u32 v4, v7, s97
	v_add_u32_e32 v4, 0, v4
	v_lshlrev_b32_e32 v5, 4, v8
	s_movk_i32 s20, 0x108
	v_cvt_pk_bf16_f32 v96, v16, v17
	v_cvt_pk_bf16_f32 v99, v0, v1
	v_mad_i64_i32 v[0:1], s[26:27], v45, s17, 0
	v_mad_i64_i32 v[16:17], s[26:27], v7, s17, 0
	v_add_u32_e32 v178, v4, v5
	v_mul_lo_u32 v4, v9, s20
	v_add_u32_e32 v5, 0, v4
	s_movk_i32 s26, 0x6800
	v_add3_u32 v179, v5, v42, s26
	v_mul_lo_u32 v5, v50, s20
	v_add_u32_e32 v6, 0, v5
	v_add3_u32 v180, v6, v42, s26
	v_or_b32_e32 v181, 32, v161
	v_or_b32_e32 v182, 64, v161
	v_or_b32_e32 v183, 0x60, v161
	v_readlane_b32 s26, v254, 35
	v_mul_u32_u24_e32 v19, 0x108, v44
	v_mad_u32_u24 v18, v44, s97, 0
	v_add_u32_e32 v21, s26, v4
	v_add_u32_e32 v22, s26, v5
	v_add_u32_e32 v23, s26, v161
	v_add_u32_e32 v24, s26, v181
	v_mov_b32_e32 v4, s26
	v_add_u32_e32 v25, s26, v182
	v_add_u32_e32 v26, s26, v183
	v_readlane_b32 s26, v254, 36
	v_mad_u32_u24 v184, v44, s20, v4
	v_add_u32_e32 v20, 0, v161
	v_add_u32_e32 v27, s26, v161
	v_add_u32_e32 v28, s26, v181
	v_mov_b32_e32 v4, s26
	v_add_u32_e32 v29, s26, v182
	v_add_u32_e32 v30, s26, v183
	s_add_u32 s26, s15, 0x1a49c300
	s_addc_u32 s27, s5, 0
	v_mad_u32_u24 v185, v44, s20, v4
	v_mov_b64_e32 v[4:5], s[26:27]
	v_mad_i64_i32 v[166:167], s[26:27], v9, s16, v[4:5]
	v_mad_i64_i32 v[168:169], s[26:27], v50, s16, v[4:5]
	v_mad_i64_i32 v[4:5], s[26:27], s4, v231, v[16:17]
	v_mad_i64_i32 v[2:3], s[26:27], s4, v231, v[2:3]
	v_mad_i64_i32 v[0:1], s[4:5], s4, v231, v[0:1]
	v_lshl_add_u64 v[174:175], v[0:1], 0, v[14:15]
	v_mov_b32_e32 v14, v221
	v_mov_b32_e32 v15, v221
	v_add_u32_e32 v186, v21, v42
	v_add_u32_e32 v187, v22, v42
	v_add_u32_e32 v188, v23, v19
	v_add_u32_e32 v16, v24, v19
	v_add_u32_e32 v17, v25, v19
	v_add_u32_e32 v21, v26, v19
	v_add_u32_e32 v22, v28, v19
	v_add_u32_e32 v23, v29, v19
	v_add_u32_e32 v24, v30, v19
	v_pk_mul_f32 v[46:47], v[46:47], s[48:49] op_sel_hi:[1,0]
	v_pk_mul_f32 v[48:49], v[48:49], s[48:49] op_sel_hi:[1,0]
	v_lshl_add_u64 v[170:171], v[4:5], 0, v[36:37]
	v_lshl_add_u64 v[172:173], v[2:3], 0, v[38:39]
	v_mov_b32_e32 v0, v221
	v_mov_b32_e32 v1, v221
	v_mov_b32_e32 v2, v221
	v_mov_b32_e32 v3, v221
	v_mov_b32_e32 v4, v221
	v_mov_b32_e32 v5, v221
	v_mov_b32_e32 v6, v221
	v_mov_b32_e32 v7, v221
	v_mov_b32_e32 v8, v221
	v_mov_b32_e32 v9, v221
	v_mov_b32_e32 v10, v221
	v_mov_b32_e32 v11, v221
	v_mov_b32_e32 v12, v221
	v_mov_b32_e32 v13, v221
	v_add_u32_e32 v189, v27, v19
	v_add_u32_e32 v190, v18, v220
	v_add_u32_e32 v191, v20, v19
	v_add_u32_e32 v194, 0x2000, v16
	v_add_u32_e32 v204, 0x2000, v17
	v_add_u32_e32 v206, 0x2000, v21
	v_add_u32_e32 v208, 0x2000, v22
	v_add_u32_e32 v210, 0x2000, v23
	v_add_u32_e32 v211, 0x2000, v24
	v_mov_b64_e32 v[30:31], v[14:15]
	v_cvt_pk_bf16_f32 v88, v46, v47
	v_cvt_pk_bf16_f32 v90, v48, v49
	v_cvt_pk_bf16_f32 v97, v32, v33
	v_cvt_pk_bf16_f32 v101, v34, v35
	v_or_b32_e32 v166, v166, v42
	v_or_b32_e32 v168, v168, v42
	s_mov_b32 s4, 0
	v_mov_b32_e32 v212, 0xf149f2ca
	v_mov_b32_e32 v213, 0
	v_mov_b64_e32 v[28:29], v[12:13]
	v_mov_b64_e32 v[26:27], v[10:11]
	v_mov_b64_e32 v[24:25], v[8:9]
	v_mov_b64_e32 v[22:23], v[6:7]
	v_mov_b64_e32 v[20:21], v[4:5]
	v_mov_b64_e32 v[18:19], v[2:3]
	v_mov_b64_e32 v[16:17], v[0:1]
	v_and_b32_e32 v200, 15, v192
	v_lshrrev_b32_e32 v201, 4, v192
	v_mul_u32_u24_e32 v179, 0x110, v201
	v_lshrrev_b32_e32 v202, 1, v200
	v_lshl_add_u32 v179, v202, 5, v179
	v_and_b32_e32 v202, 1, v200
	v_lshl_add_u32 v179, v202, 3, v179
	v_add_u32_e32 v179, 0x6800, v179
	v_add_u32_e32 v180, 0x2200, v179
	v_add_u32_e32 v186, 0xac00, v179
	v_add_u32_e32 v187, 0xac00, v180
	v_and_b32_e32 v200, 31, v192
	v_bfe_u32 v201, v192, 5, 1
	v_mul_u32_u24_e32 v191, 0x110, v200
	v_lshl_add_u32 v191, v201, 4, v191
	v_add_u32_e32 v191, 0x6800, v191
	s_waitcnt vmcnt(9)
; DI f32x16 zero16() { f32x16 z; for (int i = 0; i < 16; ++i) z[i] = 0.f; return z; }
; DI void phase_attn(const Params& p, int hf, bool skipctx, char* smem, int& rot) {
;     ...
;     f32x16 o[2]; o[0] = zero16(); o[1] = zero16();
;     float m_run = -1e30f, l_run = 0.f;
;     ...
;     ATT_WRITE(ak0, ak1, ak2, av0, av1, 0);
;     __syncthreads();
	ds_write_b128 v176, v[76:79]
	s_waitcnt vmcnt(8)
	ds_write_b128 v177, v[80:83]
	s_waitcnt vmcnt(7)
	ds_write_b128 v178, v[84:87]
	s_waitcnt vmcnt(6)
	ds_write_b64 v179, v[92:93] offset:0
	ds_write_b64 v179, v[94:95] offset:16
	s_waitcnt vmcnt(5)
	ds_write_b64 v179, v[104:105] offset:8704
	ds_write_b64 v179, v[106:107] offset:8720
	s_waitcnt lgkmcnt(0)
	s_barrier
	v_mov_b32_e32 v194, v176
	v_mov_b32_e32 v204, v177
	v_mov_b32_e32 v206, v178
	v_mov_b32_e32 v208, v179
	v_mov_b32_e32 v210, v190
	v_mov_b32_e32 v211, v191
	v_mov_b32_e32 v220, 0xf149f2ca
	v_mov_b32_e32 v176, 0
	v_mov_b32_e32 v177, 0
	v_mov_b32_e32 v178, 0
	v_mov_b32_e32 v179, 0
	v_mov_b32_e32 v180, 0
	v_mov_b32_e32 v181, 0
	v_mov_b32_e32 v182, 0
	v_mov_b32_e32 v183, 0
	v_mov_b32_e32 v184, 0
	v_mov_b32_e32 v185, 0
	v_mov_b32_e32 v186, 0
	v_mov_b32_e32 v187, 0
	v_mov_b32_e32 v188, 0
	v_mov_b32_e32 v189, 0
	v_mov_b32_e32 v190, 0
	v_mov_b32_e32 v191, 0
	v_add_u32_e32 v170, 0x18b28000, v170
	v_add_u32_e32 v172, 0x18b28000, v172
	v_add_u32_e32 v174, 0x18b28000, v174
	v_mov_b32_e32 v167, 0xbf800000
	s_mov_b32 s101, 0
	v_add_u32_e32 v169, 0xac00, v208
	v_add_u32_e32 v171, 0xce00, v208
	v_add_u32_e32 v173, 0x2200, v208

; #define MFMA(a, b, c) __builtin_amdgcn_mfma_f32_32x32x16_bf16((a), (b), (c), 0, 0, 0)
; DI float fexp2(float x) { return __builtin_amdgcn_exp2f(x); }
; DI void phase_attn(const Params& p, int hf, bool skipctx, char* smem, int& rot) {
;     ...
;         for (int ks = 0; ks < 6; ++ks)
; #pragma unroll
;           for (int kb = 0; kb < 2; ++kb) st[kb] = MFMA(kf[kb][ks], qf[ks], st[kb]);
;         __builtin_amdgcn_sched_barrier(0);
;       }
;       bf16x8 vf[2][2][2];
; #pragma unroll
;       for (int kb = 0; kb < 2; ++kb)
; #pragma unroll
;         for (int s2 = 0; s2 < 2; ++s2)
; #pragma unroll
;           for (int dvb = 0; dvb < 2; ++dvb) {
;             const char* vp = sv + (dvb * 32 + r) * VROW + (kb * 32 + 16 * s2 + 4 * h) * 2;
;             const s16x4 lo = *(const s16x4*)vp, hi = *(const s16x4*)(vp + 16);
;             vf[kb][s2][dvb] = __builtin_shufflevector(lo, hi, 0, 1, 2, 3, 4, 5, 6, 7);
;           }
;       float mx = st[0][0];
; #pragma unroll
;       for (int i = 0; i < 16; ++i) { mx = fmaxf(mx, st[0][i]); mx = fmaxf(mx, st[1][i]); }
;       if (__any(mx > m_run + 8.f)) {
;         mx = fmaxf(mx, __shfl_xor(mx, 32));
;         const float m_new = fmaxf(m_run, mx);
;         const float alpha = fexp2(m_run - m_new);
;         m_run = m_new;
;         l_run *= alpha;
; #pragma unroll
;         for (int i = 0; i < 16; ++i) { o[0][i] *= alpha; o[1][i] *= alpha; }
;       }
;       float ps = 0.f;
; #pragma unroll
;       for (int kb = 0; kb < 2; ++kb)
; #pragma unroll
;         for (int i = 0; i < 16; ++i) { const float e = fexp2(st[kb][i] - m_run); st[kb][i] = e; ps += e; }
;       l_run += ps;
; #pragma unroll
;       for (int kb = 0; kb < 2; ++kb)
; #pragma unroll
;         for (int s2 = 0; s2 < 2; ++s2) {
;           const bf16x8 pb = pack8(st[kb][8 * s2 + 0], st[kb][8 * s2 + 1], st[kb][8 * s2 + 2], st[kb][8 * s2 + 3], st[kb][8 * s2 + 4], st[kb][8 * s2 + 5], st[kb][8 * s2 + 6], st[kb][8 * s2 + 7]);
; #pragma unroll
;           for (int dvb = 0; dvb < 2; ++dvb) o[dvb] = MFMA(vf[kb][s2][dvb], pb, o[dvb]);
;     ...
;       if (kt + 2 < nkt) ATT_LOAD(ak0, ak1, ak2, av0, av1, kt + 2);
;       compute(0, 0); compute(0, 1);
;       ATT_WRITE(bk0, bk1, bk2, bv0, bv1, 1);
;       __syncthreads();
;       if (kt + 3 < nkt) ATT_LOAD(bk0, bk1, bk2, bv0, bv1, kt + 3);
;       compute(1, 0); compute(1, 1);
;       if (kt + 2 < nkt) ATT_WRITE(ak0, ak1, ak2, av0, av1, 0);
.Lsc0_mj0:
	s_waitcnt lgkmcnt(11)
	v_mfma_f32_32x32x16_bf16 v[48:63], v[36:39], v[64:67], v[176:191]
	s_waitcnt lgkmcnt(5)
	v_mfma_f32_32x32x16_bf16 v[32:47], v[40:43], v[64:67], v[176:191]
	v_mfma_f32_32x32x16_bf16 v[48:63], v[132:135], v[68:71], v[48:63]
	s_waitcnt lgkmcnt(4)
	v_mfma_f32_32x32x16_bf16 v[32:47], v[152:155], v[68:71], v[32:47]
	v_mfma_f32_32x32x16_bf16 v[48:63], v[136:139], v[72:75], v[48:63]
	s_waitcnt lgkmcnt(3)
	v_mfma_f32_32x32x16_bf16 v[32:47], v[156:159], v[72:75], v[32:47]
	v_mfma_f32_32x32x16_bf16 v[48:63], v[140:143], v[88:91], v[48:63]
	s_waitcnt lgkmcnt(2)
	v_mfma_f32_32x32x16_bf16 v[32:47], v[234:237], v[88:91], v[32:47]
	v_mfma_f32_32x32x16_bf16 v[48:63], v[144:147], v[96:99], v[48:63]
	s_waitcnt lgkmcnt(1)
	v_mfma_f32_32x32x16_bf16 v[32:47], v[238:241], v[96:99], v[32:47]
	v_mfma_f32_32x32x16_bf16 v[48:63], v[148:151], v[100:103], v[48:63]
	s_waitcnt lgkmcnt(0)
	v_mfma_f32_32x32x16_bf16 v[32:47], v[242:245], v[100:103], v[32:47]
	s_nop 3
	ds_read_b128 v[156:159], v211 offset:128
	ds_read_b128 v[148:151], v211 offset:160
	ds_read_b128 v[152:155], v211 offset:8832
	ds_read_b128 v[144:147], v211 offset:8864
	ds_read_b128 v[140:143], v211 offset:192
	ds_read_b128 v[136:139], v211 offset:8896
	ds_read_b128 v[128:131], v211 offset:224
	ds_read_b128 v[132:135], v211 offset:8928
	v_exp_f32_e32 v48, v48
	v_exp_f32_e32 v49, v49
	v_exp_f32_e32 v50, v50
	v_exp_f32_e32 v51, v51
	v_exp_f32_e32 v52, v52
	v_exp_f32_e32 v53, v53
	v_exp_f32_e32 v54, v54
	v_exp_f32_e32 v55, v55
	v_exp_f32_e32 v56, v56
	v_exp_f32_e32 v57, v57
	v_exp_f32_e32 v58, v58
	v_exp_f32_e32 v59, v59
	v_exp_f32_e32 v60, v60
	v_exp_f32_e32 v61, v61
	v_exp_f32_e32 v62, v62
	v_exp_f32_e32 v63, v63
	v_exp_f32_e32 v32, v32
	v_exp_f32_e32 v33, v33
	v_exp_f32_e32 v34, v34
	v_exp_f32_e32 v35, v35
	v_exp_f32_e32 v36, v36
	v_exp_f32_e32 v37, v37
	v_exp_f32_e32 v38, v38
	v_exp_f32_e32 v39, v39
	v_exp_f32_e32 v40, v40
	v_exp_f32_e32 v41, v41
	v_exp_f32_e32 v42, v42
	v_exp_f32_e32 v43, v43
	v_exp_f32_e32 v44, v44
	v_exp_f32_e32 v45, v45
	v_exp_f32_e32 v46, v46
	v_exp_f32_e32 v47, v47
	v_add_f32_e32 v195, v48, v49
	v_add_f32_e32 v195, v195, v50
	v_add_f32_e32 v195, v195, v51
	v_add_f32_e32 v195, v195, v52
	v_add_f32_e32 v195, v195, v53
	v_add_f32_e32 v195, v195, v54
	v_add_f32_e32 v195, v195, v55
	v_add_f32_e32 v195, v195, v56
	v_add_f32_e32 v195, v195, v57
	v_add_f32_e32 v195, v195, v58
	v_add_f32_e32 v195, v195, v59
	v_add_f32_e32 v195, v195, v60
	v_add_f32_e32 v195, v195, v61
	v_add_f32_e32 v195, v195, v62
	v_add_f32_e32 v195, v195, v63
	v_add_f32_e32 v195, v195, v32
	v_add_f32_e32 v195, v195, v33
	v_add_f32_e32 v195, v195, v34
	v_add_f32_e32 v195, v195, v35
	v_add_f32_e32 v195, v195, v36
	v_add_f32_e32 v195, v195, v37
	v_add_f32_e32 v195, v195, v38
	v_add_f32_e32 v195, v195, v39
	v_add_f32_e32 v195, v195, v40
	v_add_f32_e32 v195, v195, v41
	v_add_f32_e32 v195, v195, v42
	v_add_f32_e32 v195, v195, v43
	v_add_f32_e32 v195, v195, v44
	v_add_f32_e32 v195, v195, v45
	v_add_f32_e32 v195, v195, v46
	v_add_f32_e32 v195, v195, v47
	v_cmp_nle_f32_e32 vcc, v195, v167
	s_cbranch_vccnz .Lsc0_fb1
	v_add_f32_e32 v213, v213, v195
	v_cvt_pk_bf16_f32 v48, v48, v49
	v_cvt_pk_bf16_f32 v49, v50, v51
	v_cvt_pk_bf16_f32 v50, v52, v53
	v_cvt_pk_bf16_f32 v51, v54, v55
	v_cvt_pk_bf16_f32 v52, v56, v57
	v_cvt_pk_bf16_f32 v53, v58, v59
	v_cvt_pk_bf16_f32 v54, v60, v61
	v_cvt_pk_bf16_f32 v55, v62, v63
	v_cvt_pk_bf16_f32 v56, v32, v33
	v_cvt_pk_bf16_f32 v57, v34, v35
	v_cvt_pk_bf16_f32 v58, v36, v37
	v_cvt_pk_bf16_f32 v59, v38, v39
	v_cvt_pk_bf16_f32 v60, v40, v41
	v_cvt_pk_bf16_f32 v61, v42, v43
	v_cvt_pk_bf16_f32 v62, v44, v45
	v_cvt_pk_bf16_f32 v63, v46, v47
	s_waitcnt lgkmcnt(7)
	s_nop 0
	v_mfma_f32_32x32x16_bf16 v[16:31], v[156:159], v[48:51], v[16:31]
	s_waitcnt lgkmcnt(5)
	v_mfma_f32_32x32x16_bf16 v[0:15], v[152:155], v[48:51], v[0:15]
	s_nop 1
	v_mfma_f32_32x32x16_bf16 v[16:31], v[148:151], v[52:55], v[16:31]
	s_waitcnt lgkmcnt(4)
	v_mfma_f32_32x32x16_bf16 v[0:15], v[144:147], v[52:55], v[0:15]
	s_waitcnt lgkmcnt(3)
	s_nop 0
	v_mfma_f32_32x32x16_bf16 v[16:31], v[140:143], v[56:59], v[16:31]
	s_waitcnt lgkmcnt(2)
	v_mfma_f32_32x32x16_bf16 v[0:15], v[136:139], v[56:59], v[0:15]
	s_add_i32 s4, s4, 3
	s_cmp_ge_u32 s4, s13
	s_waitcnt lgkmcnt(1)
	v_mfma_f32_32x32x16_bf16 v[16:31], v[128:131], v[60:63], v[16:31]
	s_waitcnt vmcnt(1)
	ds_write_b128 v194, v[112:115] offset:44032
	ds_write_b128 v204, v[108:111] offset:44032
	ds_write_b128 v206, v[116:119] offset:44032
	ds_write2_b64 v169, v[120:121], v[122:123] offset1:2
	s_waitcnt vmcnt(0)
	ds_write2_b64 v171, v[124:125], v[126:127] offset1:2
	s_waitcnt lgkmcnt(0)
	s_barrier
	v_mfma_f32_32x32x16_bf16 v[0:15], v[132:135], v[60:63], v[0:15]
	s_cbranch_scc1 .LBB0_803
	v_add_u32_e32 v200, 0x6000, v174
	v_add_u32_e32 v201, 0x6000, v172
	v_add_u32_e32 v202, 0x6000, v170
	global_load_dwordx4 v[112:115], v200, s[94:95]
	global_load_dwordx4 v[108:111], v201, s[94:95]
	global_load_dwordx4 v[116:119], v202, s[94:95]
	global_load_dwordx4 v[120:123], v166, s[94:95]
	global_load_dwordx4 v[124:127], v168, s[94:95]

; #define MFMA(a, b, c) __builtin_amdgcn_mfma_f32_32x32x16_bf16((a), (b), (c), 0, 0, 0)
; DI float fexp2(float x) { return __builtin_amdgcn_exp2f(x); }
; DI void phase_attn(const Params& p, int hf, bool skipctx, char* smem, int& rot) {
;     ...
;         for (int ks = 0; ks < 6; ++ks)
; #pragma unroll
;           for (int kb = 0; kb < 2; ++kb) st[kb] = MFMA(kf[kb][ks], qf[ks], st[kb]);
;         __builtin_amdgcn_sched_barrier(0);
;       }
;       bf16x8 vf[2][2][2];
; #pragma unroll
;       for (int kb = 0; kb < 2; ++kb)
; #pragma unroll
;         for (int s2 = 0; s2 < 2; ++s2)
; #pragma unroll
;           for (int dvb = 0; dvb < 2; ++dvb) {
;             const char* vp = sv + (dvb * 32 + r) * VROW + (kb * 32 + 16 * s2 + 4 * h) * 2;
;             const s16x4 lo = *(const s16x4*)vp, hi = *(const s16x4*)(vp + 16);
;             vf[kb][s2][dvb] = __builtin_shufflevector(lo, hi, 0, 1, 2, 3, 4, 5, 6, 7);
;           }
;       float mx = st[0][0];
; #pragma unroll
;       for (int i = 0; i < 16; ++i) { mx = fmaxf(mx, st[0][i]); mx = fmaxf(mx, st[1][i]); }
;       if (__any(mx > m_run + 8.f)) {
;         mx = fmaxf(mx, __shfl_xor(mx, 32));
;         const float m_new = fmaxf(m_run, mx);
;         const float alpha = fexp2(m_run - m_new);
;         m_run = m_new;
;         l_run *= alpha;
; #pragma unroll
;         for (int i = 0; i < 16; ++i) { o[0][i] *= alpha; o[1][i] *= alpha; }
;       }
;       float ps = 0.f;
; #pragma unroll
;       for (int kb = 0; kb < 2; ++kb)
; #pragma unroll
;         for (int i = 0; i < 16; ++i) { const float e = fexp2(st[kb][i] - m_run); st[kb][i] = e; ps += e; }
;       l_run += ps;
; #pragma unroll
;       for (int kb = 0; kb < 2; ++kb)
; #pragma unroll
;         for (int s2 = 0; s2 < 2; ++s2) {
;           const bf16x8 pb = pack8(st[kb][8 * s2 + 0], st[kb][8 * s2 + 1], st[kb][8 * s2 + 2], st[kb][8 * s2 + 3], st[kb][8 * s2 + 4], st[kb][8 * s2 + 5], st[kb][8 * s2 + 6], st[kb][8 * s2 + 7]);
; #pragma unroll
;           for (int dvb = 0; dvb < 2; ++dvb) o[dvb] = MFMA(vf[kb][s2][dvb], pb, o[dvb]);
;     ...
;       compute(1, 0); compute(1, 1);
;       if (kt + 2 < nkt) ATT_WRITE(ak0, ak1, ak2, av0, av1, 0);
.Lsc0_mj2:
	s_waitcnt lgkmcnt(11)
	v_mfma_f32_32x32x16_bf16 v[48:63], v[36:39], v[64:67], v[176:191]
	s_waitcnt lgkmcnt(5)
	v_mfma_f32_32x32x16_bf16 v[32:47], v[40:43], v[64:67], v[176:191]
	v_mfma_f32_32x32x16_bf16 v[48:63], v[132:135], v[68:71], v[48:63]
	s_waitcnt lgkmcnt(4)
	v_mfma_f32_32x32x16_bf16 v[32:47], v[152:155], v[68:71], v[32:47]
	v_mfma_f32_32x32x16_bf16 v[48:63], v[136:139], v[72:75], v[48:63]
	s_waitcnt lgkmcnt(3)
	v_mfma_f32_32x32x16_bf16 v[32:47], v[156:159], v[72:75], v[32:47]
	v_mfma_f32_32x32x16_bf16 v[48:63], v[140:143], v[88:91], v[48:63]
	s_waitcnt lgkmcnt(2)
	v_mfma_f32_32x32x16_bf16 v[32:47], v[216:219], v[88:91], v[32:47]
	v_mfma_f32_32x32x16_bf16 v[48:63], v[144:147], v[96:99], v[48:63]
	s_waitcnt lgkmcnt(1)
	v_mfma_f32_32x32x16_bf16 v[32:47], v[234:237], v[96:99], v[32:47]
	v_mfma_f32_32x32x16_bf16 v[48:63], v[148:151], v[100:103], v[48:63]
	s_waitcnt lgkmcnt(0)
	v_mfma_f32_32x32x16_bf16 v[32:47], v[238:241], v[100:103], v[32:47]
	s_nop 3
	ds_read_b128 v[152:155], v211 offset:52864
	ds_read_b128 v[156:159], v211 offset:44160
	ds_read_b128 v[148:151], v211 offset:44192
	ds_read_b128 v[144:147], v211 offset:52896
	ds_read_b128 v[140:143], v211 offset:44224
	ds_read_b128 v[136:139], v211 offset:52928
	ds_read_b128 v[132:135], v211 offset:44256
	ds_read_b128 v[128:131], v211 offset:52960
	v_exp_f32_e32 v48, v48
	v_exp_f32_e32 v49, v49
	v_exp_f32_e32 v50, v50
	v_exp_f32_e32 v51, v51
	v_exp_f32_e32 v52, v52
	v_exp_f32_e32 v53, v53
	v_exp_f32_e32 v54, v54
	v_exp_f32_e32 v55, v55
	v_exp_f32_e32 v56, v56
	v_exp_f32_e32 v57, v57
	v_exp_f32_e32 v58, v58
	v_exp_f32_e32 v59, v59
	v_exp_f32_e32 v60, v60
	v_exp_f32_e32 v61, v61
	v_exp_f32_e32 v62, v62
	v_exp_f32_e32 v63, v63
	v_exp_f32_e32 v32, v32
	v_exp_f32_e32 v33, v33
	v_exp_f32_e32 v34, v34
	v_exp_f32_e32 v35, v35
	v_exp_f32_e32 v36, v36
	v_exp_f32_e32 v37, v37
	v_exp_f32_e32 v38, v38
	v_exp_f32_e32 v39, v39
	v_exp_f32_e32 v40, v40
	v_exp_f32_e32 v41, v41
	v_exp_f32_e32 v42, v42
	v_exp_f32_e32 v43, v43
	v_exp_f32_e32 v44, v44
	v_exp_f32_e32 v45, v45
	v_exp_f32_e32 v46, v46
	v_exp_f32_e32 v47, v47
	v_add_f32_e32 v195, v48, v49
	v_add_f32_e32 v195, v195, v50
	v_add_f32_e32 v195, v195, v51
	v_add_f32_e32 v195, v195, v52
	v_add_f32_e32 v195, v195, v53
	v_add_f32_e32 v195, v195, v54
	v_add_f32_e32 v195, v195, v55
	v_add_f32_e32 v195, v195, v56
	v_add_f32_e32 v195, v195, v57
	v_add_f32_e32 v195, v195, v58
	v_add_f32_e32 v195, v195, v59
	v_add_f32_e32 v195, v195, v60
	v_add_f32_e32 v195, v195, v61
	v_add_f32_e32 v195, v195, v62
	v_add_f32_e32 v195, v195, v63
	v_add_f32_e32 v195, v195, v32
	v_add_f32_e32 v195, v195, v33
	v_add_f32_e32 v195, v195, v34
	v_add_f32_e32 v195, v195, v35
	v_add_f32_e32 v195, v195, v36
	v_add_f32_e32 v195, v195, v37
	v_add_f32_e32 v195, v195, v38
	v_add_f32_e32 v195, v195, v39
	v_add_f32_e32 v195, v195, v40
	v_add_f32_e32 v195, v195, v41
	v_add_f32_e32 v195, v195, v42
	v_add_f32_e32 v195, v195, v43
	v_add_f32_e32 v195, v195, v44
	v_add_f32_e32 v195, v195, v45
	v_add_f32_e32 v195, v195, v46
	v_add_f32_e32 v195, v195, v47
	v_cmp_nle_f32_e32 vcc, v195, v167
	s_cbranch_vccnz .Lsc0_fb3
	v_add_f32_e32 v213, v213, v195
	v_cvt_pk_bf16_f32 v48, v48, v49
	v_cvt_pk_bf16_f32 v49, v50, v51
	v_cvt_pk_bf16_f32 v50, v52, v53
	v_cvt_pk_bf16_f32 v51, v54, v55
	v_cvt_pk_bf16_f32 v52, v56, v57
	v_cvt_pk_bf16_f32 v53, v58, v59
	v_cvt_pk_bf16_f32 v54, v60, v61
	v_cvt_pk_bf16_f32 v55, v62, v63
	v_cvt_pk_bf16_f32 v56, v32, v33
	v_cvt_pk_bf16_f32 v57, v34, v35
	v_cvt_pk_bf16_f32 v58, v36, v37
	v_cvt_pk_bf16_f32 v59, v38, v39
	v_cvt_pk_bf16_f32 v60, v40, v41
	v_cvt_pk_bf16_f32 v61, v42, v43
	v_cvt_pk_bf16_f32 v62, v44, v45
	v_cvt_pk_bf16_f32 v63, v46, v47
	s_waitcnt lgkmcnt(6)
	s_nop 0
	v_mfma_f32_32x32x16_bf16 v[16:31], v[156:159], v[48:51], v[16:31]
	v_mfma_f32_32x32x16_bf16 v[0:15], v[152:155], v[48:51], v[0:15]
	s_waitcnt lgkmcnt(5)
	s_nop 0
	v_mfma_f32_32x32x16_bf16 v[16:31], v[148:151], v[52:55], v[16:31]
	s_waitcnt lgkmcnt(4)
	v_mfma_f32_32x32x16_bf16 v[0:15], v[144:147], v[52:55], v[0:15]
	s_waitcnt lgkmcnt(3)
	s_nop 0
	v_mfma_f32_32x32x16_bf16 v[16:31], v[140:143], v[56:59], v[16:31]
	s_waitcnt lgkmcnt(2)
	v_mfma_f32_32x32x16_bf16 v[0:15], v[136:139], v[56:59], v[0:15]
	s_andn2_b64 vcc, exec, s[36:37]
	s_waitcnt lgkmcnt(1)
	v_mfma_f32_32x32x16_bf16 v[16:31], v[132:135], v[60:63], v[16:31]
	s_waitcnt lgkmcnt(0)
	v_mfma_f32_32x32x16_bf16 v[0:15], v[128:131], v[60:63], v[0:15]
	s_cbranch_vccnz .LBB0_809
	ds_write_b128 v194, v[76:79]
	ds_write_b128 v204, v[80:83]
	ds_write_b128 v206, v[84:87]
	ds_write2_b64 v208, v[92:93], v[94:95] offset1:2
	ds_write2_b64 v173, v[104:105], v[106:107] offset1:2

; #define MFMA(a, b, c) __builtin_amdgcn_mfma_f32_32x32x16_bf16((a), (b), (c), 0, 0, 0)
; DI float fexp2(float x) { return __builtin_amdgcn_exp2f(x); }
; DI void phase_attn(const Params& p, int hf, bool skipctx, char* smem, int& rot) {
;     ...
;         for (int i = 0; i < 16; ++i) { const float e = fexp2(st[kb][i] - m_run); st[kb][i] = e; ps += e; }
;       l_run += ps;
; #pragma unroll
;       for (int kb = 0; kb < 2; ++kb)
; #pragma unroll
;         for (int s2 = 0; s2 < 2; ++s2) {
;           const bf16x8 pb = pack8(st[kb][8 * s2 + 0], st[kb][8 * s2 + 1], st[kb][8 * s2 + 2], st[kb][8 * s2 + 3], st[kb][8 * s2 + 4], st[kb][8 * s2 + 5], st[kb][8 * s2 + 6], st[kb][8 * s2 + 7]);
; #pragma unroll
;           for (int dvb = 0; dvb < 2; ++dvb) o[dvb] = MFMA(vf[kb][s2][dvb], pb, o[dvb]);
;         }
;     ...
;       ATT_WRITE(bk0, bk1, bk2, bv0, bv1, 1);
;       __syncthreads();
;       if (kt + 3 < nkt) ATT_LOAD(bk0, bk1, bk2, bv0, bv1, kt + 3);
.Lsc0_c1_LBB0_801:
	v_exp_f32_e32 v48, v48
	v_exp_f32_e32 v49, v49
	v_exp_f32_e32 v50, v50
	v_exp_f32_e32 v51, v51
	v_exp_f32_e32 v52, v52
	v_exp_f32_e32 v53, v53
	v_exp_f32_e32 v54, v54
	v_exp_f32_e32 v55, v55
	v_cvt_pk_bf16_f32 v214, v48, v49
	v_cvt_pk_bf16_f32 v215, v50, v51
	v_cvt_pk_bf16_f32 v216, v52, v53
	v_cvt_pk_bf16_f32 v217, v54, v55
	s_waitcnt lgkmcnt(7)
	s_nop 0
	v_mfma_f32_32x32x16_bf16 v[16:31], v[156:159], v[214:217], v[16:31]
	v_exp_f32_e32 v56, v56
	s_waitcnt lgkmcnt(5)
	v_mfma_f32_32x32x16_bf16 v[0:15], v[152:155], v[214:217], v[0:15]
	v_exp_f32_e32 v57, v57
	v_exp_f32_e32 v58, v58
	v_exp_f32_e32 v59, v59
	v_exp_f32_e32 v60, v60
	v_exp_f32_e32 v61, v61
	v_exp_f32_e32 v62, v62
	v_exp_f32_e32 v63, v63
	v_cvt_pk_bf16_f32 v152, v56, v57
	v_cvt_pk_bf16_f32 v153, v58, v59
	v_cvt_pk_bf16_f32 v154, v60, v61
	v_cvt_pk_bf16_f32 v155, v62, v63
	s_nop 1
	v_mfma_f32_32x32x16_bf16 v[16:31], v[148:151], v[152:155], v[16:31]
	v_exp_f32_e32 v32, v32
	s_waitcnt lgkmcnt(4)
	v_mfma_f32_32x32x16_bf16 v[0:15], v[144:147], v[152:155], v[0:15]
	v_exp_f32_e32 v33, v33
	v_exp_f32_e32 v34, v34
	v_exp_f32_e32 v35, v35
	v_exp_f32_e32 v36, v36
	v_exp_f32_e32 v37, v37
	v_exp_f32_e32 v38, v38
	v_exp_f32_e32 v39, v39
	v_cvt_pk_bf16_f32 v144, v32, v33
	v_cvt_pk_bf16_f32 v145, v34, v35
	v_cvt_pk_bf16_f32 v146, v36, v37
	v_cvt_pk_bf16_f32 v147, v38, v39
	s_waitcnt lgkmcnt(3)
	s_nop 0
	v_mfma_f32_32x32x16_bf16 v[16:31], v[140:143], v[144:147], v[16:31]
	v_exp_f32_e32 v40, v40
	s_waitcnt lgkmcnt(2)
	v_mfma_f32_32x32x16_bf16 v[0:15], v[136:139], v[144:147], v[0:15]
	v_exp_f32_e32 v41, v41
	v_exp_f32_e32 v42, v42
	v_exp_f32_e32 v43, v43
	v_exp_f32_e32 v44, v44
	v_exp_f32_e32 v45, v45
	v_exp_f32_e32 v46, v46
	v_exp_f32_e32 v47, v47
	v_cvt_pk_bf16_f32 v136, v40, v41
	v_cvt_pk_bf16_f32 v137, v42, v43
	v_cvt_pk_bf16_f32 v138, v44, v45
	v_cvt_pk_bf16_f32 v139, v46, v47
	s_add_i32 s4, s4, 3
	s_cmp_ge_u32 s4, s13
	s_waitcnt lgkmcnt(1)
	v_mfma_f32_32x32x16_bf16 v[16:31], v[128:131], v[136:139], v[16:31]
	s_waitcnt vmcnt(1)
	ds_write_b128 v194, v[112:115] offset:44032
	ds_write_b128 v204, v[108:111] offset:44032
	ds_write_b128 v206, v[116:119] offset:44032
	ds_write2_b64 v169, v[120:121], v[122:123] offset1:2
	s_waitcnt vmcnt(0)
	ds_write2_b64 v171, v[124:125], v[126:127] offset1:2
	s_waitcnt lgkmcnt(0)
	s_barrier
	v_mfma_f32_32x32x16_bf16 v[0:15], v[132:135], v[136:139], v[0:15]
	s_cbranch_scc1 .Lsc0_c1_LBB0_803
	v_add_u32_e32 v200, 0x6000, v174
	v_add_u32_e32 v201, 0x6000, v172
	v_add_u32_e32 v202, 0x6000, v170
	global_load_dwordx4 v[112:115], v200, s[94:95]
	global_load_dwordx4 v[108:111], v201, s[94:95]
	global_load_dwordx4 v[116:119], v202, s[94:95]
	global_load_dwordx4 v[120:123], v166, s[94:95]
	global_load_dwordx4 v[124:127], v168, s[94:95]

; #define MFMA(a, b, c) __builtin_amdgcn_mfma_f32_32x32x16_bf16((a), (b), (c), 0, 0, 0)
; DI float fexp2(float x) { return __builtin_amdgcn_exp2f(x); }
; DI void phase_attn(const Params& p, int hf, bool skipctx, char* smem, int& rot) {
;     ...
;         for (int i = 0; i < 16; ++i) { const float e = fexp2(st[kb][i] - m_run); st[kb][i] = e; ps += e; }
;       l_run += ps;
; #pragma unroll
;       for (int kb = 0; kb < 2; ++kb)
; #pragma unroll
;         for (int s2 = 0; s2 < 2; ++s2) {
;           const bf16x8 pb = pack8(st[kb][8 * s2 + 0], st[kb][8 * s2 + 1], st[kb][8 * s2 + 2], st[kb][8 * s2 + 3], st[kb][8 * s2 + 4], st[kb][8 * s2 + 5], st[kb][8 * s2 + 6], st[kb][8 * s2 + 7]);
; #pragma unroll
;           for (int dvb = 0; dvb < 2; ++dvb) o[dvb] = MFMA(vf[kb][s2][dvb], pb, o[dvb]);
;         }
;     ...
;       compute(1, 0); compute(1, 1);
;       if (kt + 2 < nkt) ATT_WRITE(ak0, ak1, ak2, av0, av1, 0);
.Lsc0_c3_LBB0_807:
	v_exp_f32_e32 v48, v48
	v_exp_f32_e32 v49, v49
	v_exp_f32_e32 v50, v50
	v_exp_f32_e32 v51, v51
	v_exp_f32_e32 v52, v52
	v_exp_f32_e32 v53, v53
	v_exp_f32_e32 v54, v54
	v_exp_f32_e32 v55, v55
	v_cvt_pk_bf16_f32 v214, v48, v49
	v_cvt_pk_bf16_f32 v215, v50, v51
	v_cvt_pk_bf16_f32 v216, v52, v53
	v_cvt_pk_bf16_f32 v217, v54, v55
	s_waitcnt lgkmcnt(6)
	s_nop 0
	v_mfma_f32_32x32x16_bf16 v[16:31], v[156:159], v[214:217], v[16:31]
	v_exp_f32_e32 v56, v56
	v_mfma_f32_32x32x16_bf16 v[0:15], v[152:155], v[214:217], v[0:15]
	v_exp_f32_e32 v57, v57
	v_exp_f32_e32 v58, v58
	v_exp_f32_e32 v59, v59
	v_exp_f32_e32 v60, v60
	v_exp_f32_e32 v61, v61
	v_exp_f32_e32 v62, v62
	v_exp_f32_e32 v63, v63
	v_cvt_pk_bf16_f32 v152, v56, v57
	v_cvt_pk_bf16_f32 v153, v58, v59
	v_cvt_pk_bf16_f32 v154, v60, v61
	v_cvt_pk_bf16_f32 v155, v62, v63
	s_waitcnt lgkmcnt(5)
	s_nop 0
	v_mfma_f32_32x32x16_bf16 v[16:31], v[148:151], v[152:155], v[16:31]
	v_exp_f32_e32 v32, v32
	s_waitcnt lgkmcnt(4)
	v_mfma_f32_32x32x16_bf16 v[0:15], v[144:147], v[152:155], v[0:15]
	v_exp_f32_e32 v33, v33
	v_exp_f32_e32 v34, v34
	v_exp_f32_e32 v35, v35
	v_exp_f32_e32 v36, v36
	v_exp_f32_e32 v37, v37
	v_exp_f32_e32 v38, v38
	v_exp_f32_e32 v39, v39
	v_cvt_pk_bf16_f32 v144, v32, v33
	v_cvt_pk_bf16_f32 v145, v34, v35
	v_cvt_pk_bf16_f32 v146, v36, v37
	v_cvt_pk_bf16_f32 v147, v38, v39
	s_waitcnt lgkmcnt(3)
	s_nop 0
	v_mfma_f32_32x32x16_bf16 v[16:31], v[140:143], v[144:147], v[16:31]
	v_exp_f32_e32 v40, v40
	s_waitcnt lgkmcnt(2)
	v_mfma_f32_32x32x16_bf16 v[0:15], v[136:139], v[144:147], v[0:15]
	v_exp_f32_e32 v41, v41
	v_exp_f32_e32 v42, v42
	v_exp_f32_e32 v43, v43
	v_exp_f32_e32 v44, v44
	v_exp_f32_e32 v45, v45
	v_exp_f32_e32 v46, v46
	v_exp_f32_e32 v47, v47
	v_cvt_pk_bf16_f32 v136, v40, v41
	v_cvt_pk_bf16_f32 v137, v42, v43
	v_cvt_pk_bf16_f32 v138, v44, v45
	v_cvt_pk_bf16_f32 v139, v46, v47
	s_andn2_b64 vcc, exec, s[36:37]
	s_waitcnt lgkmcnt(1)
	v_mfma_f32_32x32x16_bf16 v[16:31], v[132:135], v[136:139], v[16:31]
	s_waitcnt lgkmcnt(0)
	v_mfma_f32_32x32x16_bf16 v[0:15], v[128:131], v[136:139], v[0:15]
	s_cbranch_vccnz .Lsc0_c3_LBB0_809
	ds_write_b128 v194, v[76:79]
	ds_write_b128 v204, v[80:83]
	ds_write_b128 v206, v[84:87]
	ds_write2_b64 v208, v[92:93], v[94:95] offset1:2
	ds_write2_b64 v173, v[104:105], v[106:107] offset1:2

; DI float bflo(unsigned u) { return __uint_as_float(u << 16); }
; DI float bfhi(unsigned u) { return __uint_as_float(u & 0xffff0000u); }
; DI void phase_attn(const Params& p, int hf, bool skipctx, char* smem, int& rot) {
;     ...
;       for (int ks = 0; ks < 6; ++ks) qu[ks] = *(const uint4*)(Qb + tq * 768 + head * 96 + ks * 16 + h * 8);
; #pragma unroll
;       for (int ks = 0; ks < 4; ++ks) {
;         const uint4 u = qu[ks];
;         qf[ks] = pack8(bflo(u.x) * QSCALE, bfhi(u.x) * QSCALE, bflo(u.y) * QSCALE, bfhi(u.y) * QSCALE, bflo(u.z) * QSCALE, bfhi(u.z) * QSCALE, bflo(u.w) * QSCALE, bfhi(u.w) * QSCALE);
;       }
;       const unsigned a1[4] = {qu[4].x, qu[4].y, qu[4].z, qu[4].w}, a2[4] = {qu[5].x, qu[5].y, qu[5].z, qu[5].w};
;       float o1[8], o2[8];
;       const int sq_ = s0 + w * 32 + r;
; #pragma unroll
;       for (int e = 0; e < 8; ++e) {
;         const float x1 = ((e & 1) ? bfhi(a1[e >> 1]) : bflo(a1[e >> 1])) * QSCALE;
;         const float x2 = ((e & 1) ? bfhi(a2[e >> 1]) : bflo(a2[e >> 1])) * QSCALE;
;         float cs = 1.f, sn = 0.f;
;         if (sq_ >= LC) { cs = axc[(sq_ - LC) * 16 + 8 * h + e]; sn = axs[(sq_ - LC) * 16 + 8 * h + e]; }
;         o1[e] = x1 * cs - x2 * sn; o2[e] = x1 * sn + x2 * cs;
;       }
;       qf[4] = pack8(o1[0], o1[1], o1[2], o1[3], o1[4], o1[5], o1[6], o1[7]);
;       qf[5] = pack8(o2[0], o2[1], o2[2], o2[3], o2[4], o2[5], o2[6], o2[7]);
;     ...
;     const int kr0 = tid / 12, kc0 = tid - kr0 * 12, kr1 = (tid + 512) / 12, kc1 = (tid + 512) - kr1 * 12, kr2 = (tid + 1024) / 12, kc2 = (tid + 1024) - kr2 * 12;
.LBB0_1059:
	s_or_b64 exec, exec, s[26:27]
	s_waitcnt vmcnt(0)
	v_lshlrev_b32_e32 v27, 16, v23
	v_lshlrev_b32_e32 v26, 16, v19
	v_pk_mul_f32 v[26:27], v[26:27], s[48:49] op_sel_hi:[1,0]
	v_lshlrev_b32_e32 v47, 16, v22
	v_pk_mul_f32 v[28:29], v[26:27], v[30:31] op_sel:[0,1] op_sel_hi:[1,0]
	v_pk_mul_f32 v[26:27], v[26:27], v[30:31]
	v_and_b32_e32 v30, 0xffff0000, v19
	v_lshlrev_b32_e32 v46, 16, v18
	v_and_b32_e32 v19, 0xffff0000, v22
	v_and_b32_e32 v18, 0xffff0000, v18
	v_and_b32_e32 v31, 0xffff0000, v23
	v_pk_mul_f32 v[46:47], v[46:47], s[48:49] op_sel_hi:[1,0]
	v_pk_mul_f32 v[22:23], v[18:19], s[48:49] op_sel_hi:[1,0]
	v_pk_mul_f32 v[48:49], v[46:47], v[42:43] op_sel:[0,1] op_sel_hi:[1,0]
	v_pk_mul_f32 v[42:43], v[46:47], v[42:43]
	v_pk_mul_f32 v[18:19], v[22:23], v[40:41] op_sel:[0,1] op_sel_hi:[1,0]
	v_pk_mul_f32 v[22:23], v[22:23], v[40:41]
	v_mov_b32_e32 v40, v42
	v_mov_b32_e32 v41, v22
	v_mov_b32_e32 v22, v43
	v_pk_add_f32 v[22:23], v[40:41], v[22:23]
	v_lshlrev_b32_e32 v41, 16, v21
	v_lshlrev_b32_e32 v40, 16, v17
	v_pk_mul_f32 v[40:41], v[40:41], s[48:49] op_sel_hi:[1,0]
	v_mov_b32_e32 v46, v48
	v_mov_b32_e32 v47, v18
	v_mov_b32_e32 v18, v49
	v_pk_mul_f32 v[42:43], v[40:41], v[32:33] op_sel:[0,1] op_sel_hi:[1,0]
	v_pk_mul_f32 v[40:41], v[40:41], v[32:33]
	v_and_b32_e32 v33, 0xffff0000, v21
	v_and_b32_e32 v32, 0xffff0000, v17
	v_pk_add_f32 v[18:19], v[46:47], v[18:19] neg_lo:[0,1] neg_hi:[0,1]
	v_pk_mul_f32 v[46:47], v[32:33], s[48:49] op_sel_hi:[1,0]
	v_mov_b32_e32 v48, v42
	v_pk_mul_f32 v[32:33], v[46:47], v[34:35] op_sel:[0,1] op_sel_hi:[1,0]
	v_pk_mul_f32 v[34:35], v[46:47], v[34:35]
	v_mov_b32_e32 v49, v32
	v_mov_b32_e32 v32, v43
	v_mov_b32_e32 v42, v40
	v_mov_b32_e32 v43, v34
	v_mov_b32_e32 v34, v41
	v_lshlrev_b32_e32 v41, 16, v20
	v_lshlrev_b32_e32 v40, 16, v16
	v_and_b32_e32 v17, 0xffff0000, v20
	v_and_b32_e32 v16, 0xffff0000, v16
	v_pk_mul_f32 v[40:41], v[40:41], s[48:49] op_sel_hi:[1,0]
	v_pk_mul_f32 v[20:21], v[16:17], s[48:49] op_sel_hi:[1,0]
	v_pk_add_f32 v[34:35], v[42:43], v[34:35]
	v_pk_mul_f32 v[42:43], v[40:41], v[38:39] op_sel:[0,1] op_sel_hi:[1,0]
	v_pk_mul_f32 v[38:39], v[40:41], v[38:39]
	v_pk_mul_f32 v[16:17], v[20:21], v[36:37] op_sel:[0,1] op_sel_hi:[1,0]
	v_pk_mul_f32 v[20:21], v[20:21], v[36:37]
	v_mov_b32_e32 v36, v38
	v_mov_b32_e32 v37, v20
	v_mov_b32_e32 v20, v39
	v_pk_add_f32 v[20:21], v[36:37], v[20:21]
	v_lshlrev_b32_e32 v36, 16, v12
	v_and_b32_e32 v37, 0xffff0000, v12
	v_lshlrev_b32_e32 v12, 16, v13
	v_and_b32_e32 v13, 0xffff0000, v13
	v_pk_mul_f32 v[12:13], v[12:13], s[48:49] op_sel_hi:[1,0]
	v_lshlrev_b32_e32 v38, 16, v14
	v_cvt_pk_bf16_f32 v65, v12, v13
	v_lshlrev_b32_e32 v12, 16, v8
	v_and_b32_e32 v13, 0xffff0000, v8
	v_lshlrev_b32_e32 v8, 16, v9
	v_and_b32_e32 v9, 0xffff0000, v9
	v_pk_mul_f32 v[8:9], v[8:9], s[48:49] op_sel_hi:[1,0]
	v_and_b32_e32 v39, 0xffff0000, v14
	v_cvt_pk_bf16_f32 v69, v8, v9
	v_lshlrev_b32_e32 v8, 16, v4
	v_and_b32_e32 v9, 0xffff0000, v4
	v_lshlrev_b32_e32 v4, 16, v5
	v_and_b32_e32 v5, 0xffff0000, v5
	v_lshlrev_b32_e32 v14, 16, v15
	v_and_b32_e32 v15, 0xffff0000, v15
	v_pk_mul_f32 v[4:5], v[4:5], s[48:49] op_sel_hi:[1,0]
	s_mov_b32 s29, 0x2aaaaaab
	v_pk_mul_f32 v[14:15], v[14:15], s[48:49] op_sel_hi:[1,0]
	v_cvt_pk_bf16_f32 v73, v4, v5
	v_mul_hi_i32 v4, v160, s29
	v_cvt_pk_bf16_f32 v67, v14, v15
	v_lshlrev_b32_e32 v14, 16, v10
	v_and_b32_e32 v15, 0xffff0000, v10
	v_lshlrev_b32_e32 v10, 16, v11
	v_and_b32_e32 v11, 0xffff0000, v11
	v_lshrrev_b32_e32 v5, 31, v4
	v_ashrrev_i32_e32 v4, 1, v4
	v_pk_mul_f32 v[10:11], v[10:11], s[48:49] op_sel_hi:[1,0]
	v_add_u32_e32 v45, v4, v5
	v_cvt_pk_bf16_f32 v71, v10, v11
	v_lshlrev_b32_e32 v10, 16, v6
	v_and_b32_e32 v11, 0xffff0000, v6
	v_lshlrev_b32_e32 v6, 16, v7
	v_and_b32_e32 v7, 0xffff0000, v7
	v_mad_u64_u32 v[4:5], s[38:39], v45, -12, v[160:161]
	v_add_u32_e32 v164, 0x200, v160
	v_pk_mul_f32 v[6:7], v[6:7], s[48:49] op_sel_hi:[1,0]
	v_mul_hi_i32 v5, v164, s29
	v_cvt_pk_bf16_f32 v75, v6, v7
	v_lshrrev_b32_e32 v6, 31, v5
	v_ashrrev_i32_e32 v5, 1, v5
	s_mul_i32 s15, s4, 0xcc000
	v_add_u32_e32 v5, v5, v6
	v_pk_mul_f32 v[38:39], v[38:39], s[48:49] op_sel_hi:[1,0]
	v_pk_mul_f32 v[14:15], v[14:15], s[48:49] op_sel_hi:[1,0]
	s_mul_hi_i32 s5, s4, 0xcc000
	s_add_u32 s26, s90, s15
	v_mad_u64_u32 v[6:7], s[38:39], v5, -12, v[164:165]
	v_add_u32_e32 v162, 0x400, v160
	v_cvt_pk_bf16_f32 v66, v38, v39
	v_cvt_pk_bf16_f32 v70, v14, v15
	v_pk_mul_f32 v[8:9], v[8:9], s[48:49] op_sel_hi:[1,0]
	v_pk_mul_f32 v[10:11], v[10:11], s[48:49] op_sel_hi:[1,0]
	s_addc_u32 s27, s91, s5
	v_mul_hi_i32 v7, v162, s29
	v_lshlrev_b32_e32 v14, 3, v4
	v_lshlrev_b32_e32 v38, 3, v6
	v_pk_mul_f32 v[36:37], v[36:37], s[48:49] op_sel_hi:[1,0]
	v_pk_mul_f32 v[12:13], v[12:13], s[48:49] op_sel_hi:[1,0]
	v_cvt_pk_bf16_f32 v72, v8, v9
	v_cvt_pk_bf16_f32 v74, v10, v11
	v_lshrrev_b32_e32 v8, 31, v7
	v_ashrrev_i32_e32 v7, 1, v7
	v_mov_b64_e32 v[10:11], s[26:27]
	v_ashrrev_i32_e32 v15, 31, v14
	v_ashrrev_i32_e32 v39, 31, v38
	v_cvt_pk_bf16_f32 v64, v36, v37
	v_cvt_pk_bf16_f32 v68, v12, v13
	v_add_u32_e32 v7, v7, v8
	v_mad_i64_i32 v[12:13], s[26:27], v45, s17, v[10:11]
	v_lshlrev_b64 v[14:15], 1, v[14:15]
	v_mad_i64_i32 v[36:37], s[26:27], v5, s17, v[10:11]
	v_lshlrev_b64 v[38:39], 1, v[38:39]
	v_mad_u64_u32 v[8:9], s[38:39], v7, -12, v[162:163]
	v_lshl_add_u64 v[12:13], v[12:13], 0, v[14:15]
	v_lshl_add_u64 v[36:37], v[36:37], 0, v[38:39]
	s_barrier
; DI f32x16 zero16() { f32x16 z; for (int i = 0; i < 16; ++i) z[i] = 0.f; return z; }
; DI void phase_attn(const Params& p, int hf, bool skipctx, char* smem, int& rot) {
;     ...
;     const bf16_t* Kg = Kb + (size_t)(bl * 8 + head) * S * 96;
;     const bf16_t* Vg = VTb + (size_t)(bl * 8 + head) * 64 * S;
;     f32x16 o[2]; o[0] = zero16(); o[1] = zero16();
;     float m_run = -1e30f, l_run = 0.f;
;     uint4 ak0, ak1, ak2, av0, av1, bk0, bk1, bk2, bv0, bv1;
;     const int kr0 = tid / 12, kc0 = tid - kr0 * 12, kr1 = (tid + 512) / 12, kc1 = (tid + 512) - kr1 * 12, kr2 = (tid + 1024) / 12, kc2 = (tid + 1024) - kr2 * 12;
;     const int vr0 = tid >> 4, vr1 = (tid + 512) >> 4, vc = tid & 15;
;     ...
;     __syncthreads();
;     ATT_LOAD(ak0, ak1, ak2, av0, av1, 0);
;     ATT_LOAD(bk0, bk1, bk2, bv0, bv1, 1);
	global_load_dwordx4 v[76:79], v[12:13], off
	global_load_dwordx4 v[80:83], v[36:37], off
	v_lshlrev_b32_e32 v36, 3, v8
	s_mul_i32 s15, s4, 0x88000
	v_readlane_b32 s36, v252, 5
	v_ashrrev_i32_e32 v37, 31, v36
	s_mul_hi_i32 s5, s4, 0x88000
	v_readlane_b32 s37, v252, 6
	s_add_u32 s36, s36, s15
	v_mad_i64_i32 v[12:13], s[26:27], v7, s17, v[10:11]
	v_lshlrev_b64 v[36:37], 1, v[36:37]
	s_addc_u32 s37, s37, s5
	v_lshl_add_u64 v[12:13], v[12:13], 0, v[36:37]
	v_mov_b32_e32 v40, v42
	v_mov_b32_e32 v41, v16
	v_mov_b32_e32 v16, v43
	v_ashrrev_i32_e32 v9, 4, v160
	v_ashrrev_i32_e32 v50, 4, v164
	global_load_dwordx4 v[84:87], v[12:13], off
	v_mov_b64_e32 v[12:13], s[36:37]
	v_lshlrev_b32_e32 v165, 4, v160
	v_cvt_pk_bf16_f32 v100, v20, v21
	v_add_u32_e32 v20, 0x80, v5
	v_pk_add_f32 v[16:17], v[40:41], v[16:17] neg_lo:[0,1] neg_hi:[0,1]
	v_mad_i64_i32 v[40:41], s[26:27], v9, s16, v[12:13]
	v_and_b32_e32 v42, 0xf0, v165
	v_mov_b32_e32 v43, v221
	v_mad_i64_i32 v[12:13], s[26:27], v50, s16, v[12:13]
	v_cvt_pk_bf16_f32 v98, v18, v19
	v_cvt_pk_bf16_f32 v102, v22, v23
	v_add_u32_e32 v18, 0x80, v45
	v_mad_i64_i32 v[20:21], s[26:27], v20, s17, v[10:11]
	v_add_u32_e32 v22, 0x80, v7
	v_lshl_add_u64 v[40:41], v[40:41], 0, v[42:43]
	v_lshl_add_u64 v[12:13], v[12:13], 0, v[42:43]
	v_mad_i64_i32 v[18:19], s[26:27], v18, s17, v[10:11]
	v_lshl_add_u64 v[20:21], v[20:21], 0, v[38:39]
	v_mad_i64_i32 v[10:11], s[26:27], v22, s17, v[10:11]
	global_load_dwordx4 v[92:95], v[40:41], off
	global_load_dwordx4 v[104:107], v[12:13], off
	v_lshl_add_u64 v[18:19], v[18:19], 0, v[14:15]
	v_lshl_add_u64 v[10:11], v[10:11], 0, v[36:37]
	global_load_dwordx4 v[108:111], v[20:21], off
	global_load_dwordx4 v[116:119], v[10:11], off
	global_load_dwordx4 v[120:123], v[40:41], off offset:256
	global_load_dwordx4 v[112:115], v[18:19], off
	global_load_dwordx4 v[124:127], v[12:13], off offset:256
	v_lshlrev_b32_e32 v46, 16, v0
	v_and_b32_e32 v47, 0xffff0000, v0
	v_lshlrev_b32_e32 v0, 16, v1
	v_and_b32_e32 v1, 0xffff0000, v1
	v_pk_mul_f32 v[30:31], v[30:31], s[48:49] op_sel_hi:[1,0]
	v_pk_add_f32 v[32:33], v[48:49], v[32:33] neg_lo:[0,1] neg_hi:[0,1]
	v_pk_mul_f32 v[0:1], v[0:1], s[48:49] op_sel_hi:[1,0]
	v_lshlrev_b32_e32 v48, 16, v2
	v_and_b32_e32 v49, 0xffff0000, v2
	v_lshlrev_b32_e32 v2, 16, v3
	v_and_b32_e32 v3, 0xffff0000, v3
	v_pk_mul_f32 v[2:3], v[2:3], s[48:49] op_sel_hi:[1,0]
	v_cvt_pk_bf16_f32 v89, v0, v1
	v_pk_mul_f32 v[0:1], v[30:31], v[24:25] op_sel:[0,1] op_sel_hi:[1,0]
	v_cvt_pk_bf16_f32 v91, v2, v3
	v_mov_b32_e32 v2, v28
	v_mov_b32_e32 v3, v0
	v_mov_b32_e32 v0, v29
	v_pk_add_f32 v[0:1], v[2:3], v[0:1] neg_lo:[0,1] neg_hi:[0,1]
	v_pk_mul_f32 v[2:3], v[30:31], v[24:25]
	v_mul_lo_u32 v10, v45, s97
	v_mov_b32_e32 v24, v26
	v_mov_b32_e32 v25, v2
	v_mov_b32_e32 v2, v27
	v_add_u32_e32 v10, 0, v10
	v_lshlrev_b32_e32 v4, 4, v4
	v_pk_add_f32 v[2:3], v[24:25], v[2:3]
	v_add_u32_e32 v176, v10, v4
	v_mul_lo_u32 v4, v5, s97
	v_cvt_pk_bf16_f32 v103, v2, v3
	v_mad_i64_i32 v[2:3], s[26:27], v5, s17, 0
	v_add_u32_e32 v4, 0, v4
	v_lshlrev_b32_e32 v5, 4, v6
	v_cvt_pk_bf16_f32 v96, v16, v17
	v_cvt_pk_bf16_f32 v99, v0, v1
	v_mad_i64_i32 v[0:1], s[26:27], v45, s17, 0
	v_mad_i64_i32 v[16:17], s[26:27], v7, s17, 0
	v_add_u32_e32 v177, v4, v5
	v_mul_lo_u32 v4, v7, s97
	v_add_u32_e32 v4, 0, v4
	v_lshlrev_b32_e32 v5, 4, v8
	s_movk_i32 s26, 0x108
	v_add_u32_e32 v178, v4, v5
	v_mul_lo_u32 v4, v9, s26
	v_add_u32_e32 v5, 0, v4
	s_movk_i32 s27, 0x6800
	v_add3_u32 v179, v5, v42, s27
	v_mul_lo_u32 v5, v50, s26
	v_add_u32_e32 v6, 0, v5
	v_add3_u32 v180, v6, v42, s27
	v_or_b32_e32 v181, 32, v161
	v_or_b32_e32 v182, 64, v161
	v_or_b32_e32 v183, 0x60, v161
	v_readlane_b32 s27, v254, 35
	v_mul_u32_u24_e32 v19, 0x108, v44
	v_mad_u32_u24 v18, v44, s97, 0
	v_add_u32_e32 v21, s27, v4
	v_add_u32_e32 v22, s27, v5
	v_add_u32_e32 v23, s27, v161
	v_add_u32_e32 v24, s27, v181
	v_mov_b32_e32 v4, s27
	v_add_u32_e32 v25, s27, v182
	v_add_u32_e32 v26, s27, v183
	v_readlane_b32 s27, v254, 36
	v_mad_u32_u24 v184, v44, s26, v4
	v_add_u32_e32 v20, 0, v161
	v_mov_b32_e32 v4, s27
	v_mad_u32_u24 v185, v44, s26, v4
	s_add_u32 s26, s15, 0x1a49c300
	v_add_u32_e32 v27, s27, v161
	v_add_u32_e32 v28, s27, v181
	v_add_u32_e32 v29, s27, v182
	v_add_u32_e32 v30, s27, v183
	s_addc_u32 s27, s5, 0
	v_mov_b64_e32 v[4:5], s[26:27]
	v_mad_i64_i32 v[166:167], s[26:27], v9, s16, v[4:5]
	v_mad_i64_i32 v[168:169], s[26:27], v50, s16, v[4:5]
	v_mad_i64_i32 v[4:5], s[26:27], s4, v231, v[16:17]
	v_mad_i64_i32 v[2:3], s[26:27], s4, v231, v[2:3]
	v_mad_i64_i32 v[0:1], s[4:5], s4, v231, v[0:1]
	v_lshl_add_u64 v[174:175], v[0:1], 0, v[14:15]
	v_mov_b32_e32 v14, v221
	v_mov_b32_e32 v15, v221
	v_add_u32_e32 v186, v21, v42
	v_add_u32_e32 v187, v22, v42
	v_add_u32_e32 v188, v23, v19
	v_add_u32_e32 v16, v24, v19
	v_add_u32_e32 v17, v25, v19
	v_add_u32_e32 v21, v26, v19
	v_add_u32_e32 v22, v28, v19
	v_add_u32_e32 v23, v29, v19
	v_add_u32_e32 v24, v30, v19
	v_pk_mul_f32 v[46:47], v[46:47], s[48:49] op_sel_hi:[1,0]
	v_pk_mul_f32 v[48:49], v[48:49], s[48:49] op_sel_hi:[1,0]
	v_lshl_add_u64 v[170:171], v[4:5], 0, v[36:37]
	v_lshl_add_u64 v[172:173], v[2:3], 0, v[38:39]
	v_mov_b32_e32 v0, v221
	v_mov_b32_e32 v1, v221
	v_mov_b32_e32 v2, v221
	v_mov_b32_e32 v3, v221
	v_mov_b32_e32 v4, v221
	v_mov_b32_e32 v5, v221
	v_mov_b32_e32 v6, v221
	v_mov_b32_e32 v7, v221
	v_mov_b32_e32 v8, v221
	v_mov_b32_e32 v9, v221
	v_mov_b32_e32 v10, v221
	v_mov_b32_e32 v11, v221
	v_mov_b32_e32 v12, v221
	v_mov_b32_e32 v13, v221
	v_add_u32_e32 v189, v27, v19
	v_add_u32_e32 v190, v18, v220
	v_add_u32_e32 v191, v20, v19
	v_add_u32_e32 v194, 0x2000, v16
	v_add_u32_e32 v204, 0x2000, v17
	v_add_u32_e32 v206, 0x2000, v21
	v_add_u32_e32 v208, 0x2000, v22
	v_add_u32_e32 v210, 0x2000, v23
	v_add_u32_e32 v211, 0x2000, v24
	v_mov_b64_e32 v[30:31], v[14:15]
	v_cvt_pk_bf16_f32 v88, v46, v47
	v_cvt_pk_bf16_f32 v90, v48, v49
	v_cvt_pk_bf16_f32 v97, v32, v33
	v_cvt_pk_bf16_f32 v101, v34, v35
	v_or_b32_e32 v166, v166, v42
	v_or_b32_e32 v168, v168, v42
	s_mov_b32 s4, 0
	v_mov_b32_e32 v212, 0xf149f2ca
	v_mov_b32_e32 v213, 0
	v_mov_b64_e32 v[28:29], v[12:13]
	v_mov_b64_e32 v[26:27], v[10:11]
	v_mov_b64_e32 v[24:25], v[8:9]
	v_mov_b64_e32 v[22:23], v[6:7]
	v_mov_b64_e32 v[20:21], v[4:5]
	v_mov_b64_e32 v[18:19], v[2:3]
	v_mov_b64_e32 v[16:17], v[0:1]
	v_and_b32_e32 v200, 15, v192
	v_lshrrev_b32_e32 v201, 4, v192
	v_mul_u32_u24_e32 v179, 0x110, v201
	v_lshrrev_b32_e32 v202, 1, v200
	v_lshl_add_u32 v179, v202, 5, v179
	v_and_b32_e32 v202, 1, v200
	v_lshl_add_u32 v179, v202, 3, v179
	v_add_u32_e32 v179, 0x6800, v179
	v_add_u32_e32 v180, 0x2200, v179
	v_add_u32_e32 v186, 0xac00, v179
	v_add_u32_e32 v187, 0xac00, v180
	v_and_b32_e32 v200, 31, v192
	v_bfe_u32 v201, v192, 5, 1
	v_mul_u32_u24_e32 v191, 0x110, v200
	v_lshl_add_u32 v191, v201, 4, v191
	v_add_u32_e32 v191, 0x6800, v191
	s_waitcnt vmcnt(9)
; DI f32x16 zero16() { f32x16 z; for (int i = 0; i < 16; ++i) z[i] = 0.f; return z; }
; DI void phase_attn(const Params& p, int hf, bool skipctx, char* smem, int& rot) {
;     ...
;     f32x16 o[2]; o[0] = zero16(); o[1] = zero16();
;     float m_run = -1e30f, l_run = 0.f;
;     ...
;     ATT_WRITE(ak0, ak1, ak2, av0, av1, 0);
;     __syncthreads();
	ds_write_b128 v176, v[76:79]
	s_waitcnt vmcnt(8)
	ds_write_b128 v177, v[80:83]
	s_waitcnt vmcnt(7)
	ds_write_b128 v178, v[84:87]
	s_waitcnt vmcnt(6)
	ds_write_b64 v179, v[92:93] offset:0
	ds_write_b64 v179, v[94:95] offset:16
	s_waitcnt vmcnt(5)
	ds_write_b64 v179, v[104:105] offset:8704
	ds_write_b64 v179, v[106:107] offset:8720
	s_waitcnt lgkmcnt(0)
	s_barrier
	v_mov_b32_e32 v194, v176
	v_mov_b32_e32 v204, v177
	v_mov_b32_e32 v206, v178
	v_mov_b32_e32 v208, v179
	v_mov_b32_e32 v210, v190
	v_mov_b32_e32 v211, v191
	v_mov_b32_e32 v220, 0xf149f2ca
	v_mov_b32_e32 v176, 0
	v_mov_b32_e32 v177, 0
	v_mov_b32_e32 v178, 0
	v_mov_b32_e32 v179, 0
	v_mov_b32_e32 v180, 0
	v_mov_b32_e32 v181, 0
	v_mov_b32_e32 v182, 0
	v_mov_b32_e32 v183, 0
	v_mov_b32_e32 v184, 0
	v_mov_b32_e32 v185, 0
	v_mov_b32_e32 v186, 0
	v_mov_b32_e32 v187, 0
	v_mov_b32_e32 v188, 0
	v_mov_b32_e32 v189, 0
	v_mov_b32_e32 v190, 0
	v_mov_b32_e32 v191, 0
	v_add_u32_e32 v170, 0x18b28000, v170
	v_add_u32_e32 v172, 0x18b28000, v172
	v_add_u32_e32 v174, 0x18b28000, v174
	v_mov_b32_e32 v167, 0xbf800000
	s_mov_b32 s101, 0
	v_add_u32_e32 v169, 0xac00, v208
	v_add_u32_e32 v171, 0xce00, v208
	v_add_u32_e32 v173, 0x2200, v208
